# down epilogue: 14 of 16 residual loads issued up front (counted vmcnt(13)), last block unchanged
# speedup vs baseline: 1.0905x; 1.0065x over previous
; #define G8_STAGE(bufoff, gbase) do { _Pragma("unroll") for (int _i = 0; _i < 2; ++_i) \
;     __builtin_amdgcn_global_load_lds((const unsigned*)((const char*)(gbase) + voffA[_i]), (LAS unsigned*)(lds + (bufoff) + ldsw + _i * 8192), 16, 0, 0); } while (0)
; #define G8_LDA(dst, b, h) do { _Pragma("unroll") for (int m = 0; m < 4; ++m) _Pragma("unroll") for (int k = 0; k < 2; ++k) dst[m][k] = *(const LAS h16x8*)(lds + G8_SA(b, h) + aoff + m * 2048 + k * 1024); } while (0)
; #define G8_LDB(dst, b, h) do { _Pragma("unroll") for (int n = 0; n < 2; ++n) _Pragma("unroll") for (int k = 0; k < 2; ++k) dst[n][k] = *(const LAS h16x8*)(lds + G8_SB(b, h) + boff + n * 2048 + k * 1024); } while (0)
; #define G8_MMA(ai, bj, At, Bt_) do { __builtin_amdgcn_s_setprio(1); _Pragma("unroll") for (int m = 0; m < 4; ++m) _Pragma("unroll") for (int n = 0; n < 2; ++n) _Pragma("unroll") for (int k = 0; k < 2; ++k) \
;     acc[ai][bj][m][n] = __builtin_amdgcn_mfma_f32_16x16x32_f16(Bt_[n][k], At[m][k], acc[ai][bj][m][n], 0, 0, 0); __builtin_amdgcn_s_setprio(0); } while (0)
; #define G8_WAIT_V(n) asm volatile("s_waitcnt vmcnt(" #n ")" ::: "memory")
; #define G8_WAIT_L(n) asm volatile("s_waitcnt lgkmcnt(" #n ")" ::: "memory")
; #define G8_BAR __builtin_amdgcn_s_barrier()
; #define G8_SCHED __builtin_amdgcn_sched_barrier(0)
; template <class Epi>
; __device__ __forceinline__ void gemm_phase(LAS unsigned char* lds, const h16* A, const h16* Bt, int K, const Order& S, const Epi& E) {
;     ...
;       G8_LDB(B0, 0, 0); G8_SCHED; G8_LDA(At, 0, 0); G8_STAGE(G8_SA(1, 1), a1 + hstep);
;       G8_WAIT_L(8); G8_BAR; G8_WAIT_L(0); G8_MMA(0, 0, At, B0); G8_BAR; G8_SCHED;
;       G8_LDB(B1, 0, 1); G8_STAGE(G8_SB(0, 0), b2);
;       G8_BAR; G8_WAIT_L(0); G8_MMA(0, 1, At, B1); G8_BAR;
;       G8_LDA(At, 0, 1); G8_STAGE(G8_SA(0, 0), a2);
;       G8_BAR; G8_WAIT_L(0); G8_MMA(1, 0, At, B0); G8_BAR; G8_SCHED;
;       G8_STAGE(G8_SB(0, 1), b2 + hstep);
;       G8_WAIT_V(6); G8_BAR; G8_MMA(1, 1, At, B1); G8_BAR;
.LBB0_2542:
	v_or_b32_e32 v140, 0x10000, v158
	v_add_u32_e32 v141, 0x10400, v158
	ds_read_b128 v[152:155], v140
	ds_read_b128 v[160:163], v141
	v_add_u32_e32 v140, 0x10800, v158
	v_add_u32_e32 v141, 0x10c00, v158
	ds_read_b128 v[164:167], v140
	ds_read_b128 v[168:171], v141
	s_add_u32 s24, s22, 0xfff00080
	s_addc_u32 s25, s23, -1
	s_cmp_eq_u32 s53, 60
	s_cselect_b32 s27, s3, s25
	s_cselect_b32 s26, s9, s24
	s_cselect_b32 s25, s15, s52
	s_cselect_b32 s24, s17, s51
	v_lshl_add_u64 v[140:141], s[22:23], 0, v[136:137]
	s_add_i32 m0, s35, 0xc000
	ds_read_b128 v[172:175], v135
	ds_read_b128 v[176:179], v135 offset:1024
	ds_read_b128 v[180:183], v135 offset:2048
	ds_read_b128 v[184:187], v135 offset:3072
	ds_read_b128 v[202:205], v135 offset:4096
	ds_read_b128 v[206:209], v135 offset:5120
	ds_read_b128 v[210:213], v135 offset:6144
	ds_read_b128 v[214:217], v135 offset:7168
	global_load_lds_dwordx4 v[140:141], off
	v_lshl_add_u64 v[140:141], s[22:23], 0, v[138:139]
	s_add_i32 m0, s35, 0xe000
	s_nop 0
	global_load_lds_dwordx4 v[140:141], off
	s_waitcnt lgkmcnt(8)
	s_barrier
	s_waitcnt lgkmcnt(0)
	s_setprio 1
	s_waitcnt lgkmcnt(0)
	v_mfma_f32_16x16x32_f16 v[126:129], v[152:155], v[172:175], v[126:129]
	v_mfma_f32_16x16x32_f16 v[122:125], v[164:167], v[172:175], v[122:125]
	v_mfma_f32_16x16x32_f16 v[110:113], v[152:155], v[180:183], v[110:113]
	v_mfma_f32_16x16x32_f16 v[106:109], v[164:167], v[180:183], v[106:109]
	v_mfma_f32_16x16x32_f16 v[94:97], v[152:155], v[202:205], v[94:97]
	v_mfma_f32_16x16x32_f16 v[90:93], v[164:167], v[202:205], v[90:93]
	v_mfma_f32_16x16x32_f16 v[78:81], v[152:155], v[210:213], v[78:81]
	v_mfma_f32_16x16x32_f16 v[74:77], v[164:167], v[210:213], v[74:77]
	v_mfma_f32_16x16x32_f16 v[126:129], v[160:163], v[176:179], v[126:129]
	v_mfma_f32_16x16x32_f16 v[122:125], v[168:171], v[176:179], v[122:125]
	v_mfma_f32_16x16x32_f16 v[110:113], v[160:163], v[184:187], v[110:113]
	v_mfma_f32_16x16x32_f16 v[106:109], v[168:171], v[184:187], v[106:109]
	v_mfma_f32_16x16x32_f16 v[94:97], v[160:163], v[206:209], v[94:97]
	v_mfma_f32_16x16x32_f16 v[90:93], v[168:171], v[206:209], v[90:93]
	v_mfma_f32_16x16x32_f16 v[78:81], v[160:163], v[214:217], v[78:81]
	v_mfma_f32_16x16x32_f16 v[74:77], v[168:171], v[214:217], v[74:77]
	s_setprio 0
	s_barrier
	v_or_b32_e32 v140, 0x14000, v158
	v_add_u32_e32 v141, 0x14400, v158
	ds_read_b128 v[218:221], v140
	ds_read_b128 v[222:225], v141
	v_add_u32_e32 v140, 0x14800, v158
	v_add_u32_e32 v141, 0x14c00, v158
	s_mov_b32 m0, s36
	ds_read_b128 v[226:229], v140
	ds_read_b128 v[230:233], v141
	v_lshl_add_u64 v[140:141], s[24:25], 0, v[0:1]
	global_load_lds_dwordx4 v[140:141], off
	v_lshl_add_u64 v[156:157], s[24:25], 0, v[130:131]
	s_mov_b32 m0, s37
	s_nop 0
	global_load_lds_dwordx4 v[156:157], off
	s_barrier
	s_waitcnt lgkmcnt(0)
	s_setprio 1
	s_waitcnt lgkmcnt(0)
	v_mfma_f32_16x16x32_f16 v[118:121], v[218:221], v[172:175], v[118:121]
	v_mfma_f32_16x16x32_f16 v[114:117], v[226:229], v[172:175], v[114:117]
	v_mfma_f32_16x16x32_f16 v[102:105], v[218:221], v[180:183], v[102:105]
	v_mfma_f32_16x16x32_f16 v[98:101], v[226:229], v[180:183], v[98:101]
	v_mfma_f32_16x16x32_f16 v[86:89], v[218:221], v[202:205], v[86:89]
	v_mfma_f32_16x16x32_f16 v[82:85], v[226:229], v[202:205], v[82:85]
	v_mfma_f32_16x16x32_f16 v[70:73], v[218:221], v[210:213], v[70:73]
	v_mfma_f32_16x16x32_f16 v[66:69], v[226:229], v[210:213], v[66:69]
	v_mfma_f32_16x16x32_f16 v[118:121], v[222:225], v[176:179], v[118:121]
	v_mfma_f32_16x16x32_f16 v[114:117], v[230:233], v[176:179], v[114:117]
	v_mfma_f32_16x16x32_f16 v[102:105], v[222:225], v[184:187], v[102:105]
	v_mfma_f32_16x16x32_f16 v[98:101], v[230:233], v[184:187], v[98:101]
	v_mfma_f32_16x16x32_f16 v[86:89], v[222:225], v[206:209], v[86:89]
	v_mfma_f32_16x16x32_f16 v[82:85], v[230:233], v[206:209], v[82:85]
	v_mfma_f32_16x16x32_f16 v[70:73], v[222:225], v[214:217], v[70:73]
	v_mfma_f32_16x16x32_f16 v[66:69], v[230:233], v[214:217], v[66:69]
	s_setprio 0
	s_mov_b32 m0, s35
	v_lshl_add_u64 v[188:189], s[26:27], 0, v[0:1]
	s_barrier
	ds_read_b128 v[172:175], v135 offset:16384
	ds_read_b128 v[176:179], v135 offset:17408
	ds_read_b128 v[180:183], v135 offset:18432
	ds_read_b128 v[184:187], v135 offset:19456
	ds_read_b128 v[202:205], v135 offset:20480
	ds_read_b128 v[206:209], v135 offset:21504
	ds_read_b128 v[210:213], v135 offset:22528
	ds_read_b128 v[214:217], v135 offset:23552
	global_load_lds_dwordx4 v[188:189], off
	v_lshl_add_u64 v[234:235], s[26:27], 0, v[130:131]
	s_mov_b32 m0, s38
	s_nop 0
	global_load_lds_dwordx4 v[234:235], off
	s_barrier
	s_waitcnt lgkmcnt(0)
	s_setprio 1
	s_waitcnt lgkmcnt(0)
	v_mfma_f32_16x16x32_f16 v[62:65], v[152:155], v[172:175], v[62:65]
	v_mfma_f32_16x16x32_f16 v[58:61], v[164:167], v[172:175], v[58:61]
	v_mfma_f32_16x16x32_f16 v[46:49], v[152:155], v[180:183], v[46:49]
	v_mfma_f32_16x16x32_f16 v[42:45], v[164:167], v[180:183], v[42:45]
	v_mfma_f32_16x16x32_f16 v[30:33], v[152:155], v[202:205], v[30:33]
	v_mfma_f32_16x16x32_f16 v[26:29], v[164:167], v[202:205], v[26:29]
	v_mfma_f32_16x16x32_f16 v[14:17], v[152:155], v[210:213], v[14:17]
	v_mfma_f32_16x16x32_f16 v[10:13], v[164:167], v[210:213], v[10:13]
	v_mfma_f32_16x16x32_f16 v[62:65], v[160:163], v[176:179], v[62:65]
	v_mfma_f32_16x16x32_f16 v[58:61], v[168:171], v[176:179], v[58:61]
	v_mfma_f32_16x16x32_f16 v[46:49], v[160:163], v[184:187], v[46:49]
	v_mfma_f32_16x16x32_f16 v[42:45], v[168:171], v[184:187], v[42:45]
	v_mfma_f32_16x16x32_f16 v[30:33], v[160:163], v[206:209], v[30:33]
	v_mfma_f32_16x16x32_f16 v[26:29], v[168:171], v[206:209], v[26:29]
	v_mfma_f32_16x16x32_f16 v[14:17], v[160:163], v[214:217], v[14:17]
	v_mfma_f32_16x16x32_f16 v[10:13], v[168:171], v[214:217], v[10:13]
	s_setprio 0
	s_barrier
; #define G8_STAGE(bufoff, gbase) do { _Pragma("unroll") for (int _i = 0; _i < 2; ++_i) \
;     __builtin_amdgcn_global_load_lds((const unsigned*)((const char*)(gbase) + voffA[_i]), (LAS unsigned*)(lds + (bufoff) + ldsw + _i * 8192), 16, 0, 0); } while (0)
; #define G8_LDA(dst, b, h) do { _Pragma("unroll") for (int m = 0; m < 4; ++m) _Pragma("unroll") for (int k = 0; k < 2; ++k) dst[m][k] = *(const LAS h16x8*)(lds + G8_SA(b, h) + aoff + m * 2048 + k * 1024); } while (0)
; #define G8_LDB(dst, b, h) do { _Pragma("unroll") for (int n = 0; n < 2; ++n) _Pragma("unroll") for (int k = 0; k < 2; ++k) dst[n][k] = *(const LAS h16x8*)(lds + G8_SB(b, h) + boff + n * 2048 + k * 1024); } while (0)
; #define G8_MMA(ai, bj, At, Bt_) do { __builtin_amdgcn_s_setprio(1); _Pragma("unroll") for (int m = 0; m < 4; ++m) _Pragma("unroll") for (int n = 0; n < 2; ++n) _Pragma("unroll") for (int k = 0; k < 2; ++k) \
;     acc[ai][bj][m][n] = __builtin_amdgcn_mfma_f32_16x16x32_f16(Bt_[n][k], At[m][k], acc[ai][bj][m][n], 0, 0, 0); __builtin_amdgcn_s_setprio(0); } while (0)
; #define G8_WAIT_V(n) asm volatile("s_waitcnt vmcnt(" #n ")" ::: "memory")
; #define G8_WAIT_L(n) asm volatile("s_waitcnt lgkmcnt(" #n ")" ::: "memory")
; #define G8_BAR __builtin_amdgcn_s_barrier()
; #define G8_SCHED __builtin_amdgcn_sched_barrier(0)
; template <class Epi>
; __device__ __forceinline__ void gemm_phase(LAS unsigned char* lds, const h16* A, const h16* Bt, int K, const Order& S, const Epi& E) {
;     ...
;       G8_WAIT_V(6); G8_BAR; G8_MMA(1, 1, At, B1); G8_BAR;
;       G8_LDB(B0, 1, 0); G8_SCHED; G8_LDA(At, 1, 0); G8_STAGE(G8_SA(0, 1), a2 + hstep);
;       G8_WAIT_L(8); G8_BAR; G8_WAIT_L(0); G8_MMA(0, 0, At, B0); G8_BAR; G8_SCHED;
;       G8_LDB(B1, 1, 1); G8_STAGE(G8_SB(1, 0), b3);
;       G8_BAR; G8_WAIT_L(0); G8_MMA(0, 1, At, B1); G8_BAR;
;       G8_LDA(At, 1, 1); G8_STAGE(G8_SA(1, 0), a3);
;       G8_BAR; G8_WAIT_L(0); G8_MMA(1, 0, At, B0); G8_BAR; G8_SCHED;
	s_add_u32 s54, s24, 0x100000
	s_addc_u32 s55, s25, 0
	s_mov_b32 m0, s39
	v_lshl_add_u64 v[152:153], s[54:55], 0, v[0:1]
	global_load_lds_dwordx4 v[152:153], off
	v_lshl_add_u64 v[152:153], s[54:55], 0, v[130:131]
	s_mov_b32 m0, s40
	s_nop 0
	global_load_lds_dwordx4 v[152:153], off
	s_waitcnt vmcnt(6)
	s_barrier
	s_setprio 1
	v_mfma_f32_16x16x32_f16 v[54:57], v[218:221], v[172:175], v[54:57]
	v_mfma_f32_16x16x32_f16 v[50:53], v[226:229], v[172:175], v[50:53]
	v_mfma_f32_16x16x32_f16 v[38:41], v[218:221], v[180:183], v[38:41]
	v_mfma_f32_16x16x32_f16 v[34:37], v[226:229], v[180:183], v[34:37]
	v_mfma_f32_16x16x32_f16 v[22:25], v[218:221], v[202:205], v[22:25]
	v_mfma_f32_16x16x32_f16 v[18:21], v[226:229], v[202:205], v[18:21]
	v_mfma_f32_16x16x32_f16 v[6:9], v[218:221], v[210:213], v[6:9]
	v_mfma_f32_16x16x32_f16 v[2:5], v[226:229], v[210:213], v[2:5]
	v_mfma_f32_16x16x32_f16 v[54:57], v[222:225], v[176:179], v[54:57]
	v_mfma_f32_16x16x32_f16 v[50:53], v[230:233], v[176:179], v[50:53]
	v_mfma_f32_16x16x32_f16 v[38:41], v[222:225], v[184:187], v[38:41]
	v_mfma_f32_16x16x32_f16 v[34:37], v[230:233], v[184:187], v[34:37]
	v_mfma_f32_16x16x32_f16 v[22:25], v[222:225], v[206:209], v[22:25]
	v_mfma_f32_16x16x32_f16 v[18:21], v[230:233], v[206:209], v[18:21]
	v_mfma_f32_16x16x32_f16 v[6:9], v[222:225], v[214:217], v[6:9]
	v_mfma_f32_16x16x32_f16 v[2:5], v[230:233], v[214:217], v[2:5]
	s_setprio 0
	v_or_b32_e32 v152, 0x18000, v158
	v_add_u32_e32 v159, 0x18400, v158
	s_barrier
	ds_read_b128 v[152:155], v152
	ds_read_b128 v[160:163], v159
	v_add_u32_e32 v159, 0x18800, v158
	v_add_u32_e32 v168, 0x18c00, v158
	ds_read_b128 v[164:167], v159
	ds_read_b128 v[168:171], v168
	s_add_u32 s26, s26, 0x100000
	s_addc_u32 s27, s27, 0
	s_mov_b32 m0, s41
	v_lshl_add_u64 v[218:219], s[26:27], 0, v[0:1]
	ds_read_b128 v[172:175], v135 offset:32768
	ds_read_b128 v[176:179], v135 offset:33792
	ds_read_b128 v[180:183], v135 offset:34816
	ds_read_b128 v[184:187], v135 offset:35840
	ds_read_b128 v[202:205], v135 offset:36864
	ds_read_b128 v[206:209], v135 offset:37888
	ds_read_b128 v[210:213], v135 offset:38912
	ds_read_b128 v[214:217], v135 offset:39936
	global_load_lds_dwordx4 v[218:219], off
	v_lshl_add_u64 v[218:219], s[26:27], 0, v[130:131]
	s_mov_b32 m0, s42
	s_nop 0
	global_load_lds_dwordx4 v[218:219], off
	s_waitcnt lgkmcnt(8)
	s_barrier
	s_waitcnt lgkmcnt(0)
	s_setprio 1
	s_waitcnt lgkmcnt(0)
	v_mfma_f32_16x16x32_f16 v[126:129], v[152:155], v[172:175], v[126:129]
	v_mfma_f32_16x16x32_f16 v[122:125], v[164:167], v[172:175], v[122:125]
	v_mfma_f32_16x16x32_f16 v[110:113], v[152:155], v[180:183], v[110:113]
	v_mfma_f32_16x16x32_f16 v[106:109], v[164:167], v[180:183], v[106:109]
	v_mfma_f32_16x16x32_f16 v[94:97], v[152:155], v[202:205], v[94:97]
	v_mfma_f32_16x16x32_f16 v[90:93], v[164:167], v[202:205], v[90:93]
	v_mfma_f32_16x16x32_f16 v[78:81], v[152:155], v[210:213], v[78:81]
	v_mfma_f32_16x16x32_f16 v[74:77], v[164:167], v[210:213], v[74:77]
	v_mfma_f32_16x16x32_f16 v[126:129], v[160:163], v[176:179], v[126:129]
	v_mfma_f32_16x16x32_f16 v[122:125], v[168:171], v[176:179], v[122:125]
	v_mfma_f32_16x16x32_f16 v[110:113], v[160:163], v[184:187], v[110:113]
	v_mfma_f32_16x16x32_f16 v[106:109], v[168:171], v[184:187], v[106:109]
	v_mfma_f32_16x16x32_f16 v[94:97], v[160:163], v[206:209], v[94:97]
	v_mfma_f32_16x16x32_f16 v[90:93], v[168:171], v[206:209], v[90:93]
	v_mfma_f32_16x16x32_f16 v[78:81], v[160:163], v[214:217], v[78:81]
	v_mfma_f32_16x16x32_f16 v[74:77], v[168:171], v[214:217], v[74:77]
	s_setprio 0
	s_barrier
	v_or_b32_e32 v159, 0x1c000, v158
	s_mov_b32 m0, s44
	v_add_u32_e32 v195, 0x1c400, v158
	ds_read_b128 v[218:221], v159
	ds_read_b128 v[222:225], v195
	v_add_u32_e32 v159, 0x1c800, v158
	v_lshl_add_u64 v[140:141], v[140:141], 0, s[94:95]
	v_add_u32_e32 v195, 0x1cc00, v158
	ds_read_b128 v[226:229], v159
	ds_read_b128 v[230:233], v195
	global_load_lds_dwordx4 v[140:141], off
	v_lshl_add_u64 v[140:141], v[156:157], 0, s[94:95]
	s_mov_b32 m0, s45
	s_nop 0
	global_load_lds_dwordx4 v[140:141], off
	s_barrier
	s_waitcnt lgkmcnt(0)
	s_setprio 1
	s_waitcnt lgkmcnt(0)
	v_mfma_f32_16x16x32_f16 v[118:121], v[218:221], v[172:175], v[118:121]
	v_mfma_f32_16x16x32_f16 v[114:117], v[226:229], v[172:175], v[114:117]
	v_mfma_f32_16x16x32_f16 v[102:105], v[218:221], v[180:183], v[102:105]
	v_mfma_f32_16x16x32_f16 v[98:101], v[226:229], v[180:183], v[98:101]
	v_mfma_f32_16x16x32_f16 v[86:89], v[218:221], v[202:205], v[86:89]
	v_mfma_f32_16x16x32_f16 v[82:85], v[226:229], v[202:205], v[82:85]
	v_mfma_f32_16x16x32_f16 v[70:73], v[218:221], v[210:213], v[70:73]
	v_mfma_f32_16x16x32_f16 v[66:69], v[226:229], v[210:213], v[66:69]
	v_mfma_f32_16x16x32_f16 v[118:121], v[222:225], v[176:179], v[118:121]
	v_mfma_f32_16x16x32_f16 v[114:117], v[230:233], v[176:179], v[114:117]
	v_mfma_f32_16x16x32_f16 v[102:105], v[222:225], v[184:187], v[102:105]
	v_mfma_f32_16x16x32_f16 v[98:101], v[230:233], v[184:187], v[98:101]
	v_mfma_f32_16x16x32_f16 v[86:89], v[222:225], v[206:209], v[86:89]
	v_mfma_f32_16x16x32_f16 v[82:85], v[230:233], v[206:209], v[82:85]
	v_mfma_f32_16x16x32_f16 v[70:73], v[222:225], v[214:217], v[70:73]
	v_mfma_f32_16x16x32_f16 v[66:69], v[230:233], v[214:217], v[66:69]
	s_setprio 0
	s_mov_b32 m0, s46
	v_lshl_add_u64 v[140:141], v[188:189], 0, s[94:95]
	s_barrier
; #define G8_STAGE(bufoff, gbase) do { _Pragma("unroll") for (int _i = 0; _i < 2; ++_i) \
;     __builtin_amdgcn_global_load_lds((const unsigned*)((const char*)(gbase) + voffA[_i]), (LAS unsigned*)(lds + (bufoff) + ldsw + _i * 8192), 16, 0, 0); } while (0)
; #define G8_MMA(ai, bj, At, Bt_) do { __builtin_amdgcn_s_setprio(1); _Pragma("unroll") for (int m = 0; m < 4; ++m) _Pragma("unroll") for (int n = 0; n < 2; ++n) _Pragma("unroll") for (int k = 0; k < 2; ++k) \
;     acc[ai][bj][m][n] = __builtin_amdgcn_mfma_f32_16x16x32_f16(Bt_[n][k], At[m][k], acc[ai][bj][m][n], 0, 0, 0); __builtin_amdgcn_s_setprio(0); } while (0)
; #define G8_WAIT_V(n) asm volatile("s_waitcnt vmcnt(" #n ")" ::: "memory")
; #define G8_WAIT_L(n) asm volatile("s_waitcnt lgkmcnt(" #n ")" ::: "memory")
; #define G8_BAR __builtin_amdgcn_s_barrier()
; #define G8_SCHED __builtin_amdgcn_sched_barrier(0)
; template <class Epi>
; __device__ __forceinline__ void gemm_phase(LAS unsigned char* lds, const h16* A, const h16* Bt, int K, const Order& S, const Epi& E) {
;     ...
;       G8_BAR; G8_WAIT_L(0); G8_MMA(1, 0, At, B0); G8_BAR; G8_SCHED;
;       G8_STAGE(G8_SB(1, 1), b3 + hstep);
;       G8_WAIT_V(6); G8_BAR; G8_MMA(1, 1, At, B1); G8_BAR;
;   __device__ __forceinline__ void operator()(const f32x4 (&acc)[2][2][4][2], const g8::Unit& u, int ui, int wr, int wc, int fr, int fq) const {
;     ...
;         const size_t row = (size_t)u.pm * 256 + 128 * ai + 64 * wr + 16 * m + fr;
;         const size_t base = row * DM + 256 * u.pn + 32 * wc + 8 * fq;
;         float ss = 0.f;
; #pragma unroll
;         for (int bj = 0; bj < 2; ++bj) {
;           const size_t idx = base + 128 * bj;
;           const h16x8 xv = *(const h16x8*)(xb + idx);
;           f32x4 x0 = acc[ai][bj][m][0], x1 = acc[ai][bj][m][1];
; #pragma unroll
;           for (int j = 0; j < 4; ++j) { x0[j] += (float)xv[j]; x1[j] += (float)xv[4 + j]; ss += x0[j] * x0[j] + x1[j] * x1[j]; }
	ds_read_b128 v[172:175], v135 offset:49152
	ds_read_b128 v[176:179], v135 offset:50176
	ds_read_b128 v[180:183], v135 offset:51200
	ds_read_b128 v[184:187], v135 offset:52224
	ds_read_b128 v[202:205], v135 offset:53248
	ds_read_b128 v[206:209], v135 offset:54272
	ds_read_b128 v[210:213], v135 offset:55296
	ds_read_b128 v[214:217], v135 offset:56320
	global_load_lds_dwordx4 v[140:141], off
	v_lshl_add_u64 v[140:141], v[234:235], 0, s[94:95]
	s_mov_b32 m0, s47
	s_nop 0
	global_load_lds_dwordx4 v[140:141], off
	s_barrier
	s_waitcnt lgkmcnt(0)
	s_setprio 1
	s_waitcnt lgkmcnt(0)
	v_mfma_f32_16x16x32_f16 v[62:65], v[152:155], v[172:175], v[62:65]
	v_mfma_f32_16x16x32_f16 v[58:61], v[164:167], v[172:175], v[58:61]
	v_mfma_f32_16x16x32_f16 v[46:49], v[152:155], v[180:183], v[46:49]
	v_mfma_f32_16x16x32_f16 v[42:45], v[164:167], v[180:183], v[42:45]
	v_mfma_f32_16x16x32_f16 v[30:33], v[152:155], v[202:205], v[30:33]
	v_mfma_f32_16x16x32_f16 v[26:29], v[164:167], v[202:205], v[26:29]
	v_mfma_f32_16x16x32_f16 v[14:17], v[152:155], v[210:213], v[14:17]
	v_mfma_f32_16x16x32_f16 v[10:13], v[164:167], v[210:213], v[10:13]
	v_mfma_f32_16x16x32_f16 v[62:65], v[160:163], v[176:179], v[62:65]
	v_mfma_f32_16x16x32_f16 v[58:61], v[168:171], v[176:179], v[58:61]
	v_mfma_f32_16x16x32_f16 v[46:49], v[160:163], v[184:187], v[46:49]
	v_mfma_f32_16x16x32_f16 v[42:45], v[168:171], v[184:187], v[42:45]
	v_mfma_f32_16x16x32_f16 v[30:33], v[160:163], v[206:209], v[30:33]
	v_mfma_f32_16x16x32_f16 v[26:29], v[168:171], v[206:209], v[26:29]
	v_mfma_f32_16x16x32_f16 v[14:17], v[160:163], v[214:217], v[14:17]
	v_mfma_f32_16x16x32_f16 v[10:13], v[168:171], v[214:217], v[10:13]
	s_setprio 0
	s_barrier
	s_add_u32 s24, s24, 0x100080
	s_addc_u32 s25, s25, 0
	s_mov_b32 m0, s48
	v_lshl_add_u64 v[140:141], s[24:25], 0, v[0:1]
	global_load_lds_dwordx4 v[140:141], off
	v_lshl_add_u64 v[140:141], s[24:25], 0, v[130:131]
	s_mov_b32 m0, s49
	s_nop 0
	global_load_lds_dwordx4 v[140:141], off
	s_waitcnt vmcnt(6)
	s_barrier
	s_setprio 1
	v_mfma_f32_16x16x32_f16 v[54:57], v[218:221], v[172:175], v[54:57]
	v_mfma_f32_16x16x32_f16 v[50:53], v[226:229], v[172:175], v[50:53]
	v_mfma_f32_16x16x32_f16 v[38:41], v[218:221], v[180:183], v[38:41]
	v_mfma_f32_16x16x32_f16 v[34:37], v[226:229], v[180:183], v[34:37]
	v_mfma_f32_16x16x32_f16 v[22:25], v[218:221], v[202:205], v[22:25]
	v_mfma_f32_16x16x32_f16 v[18:21], v[226:229], v[202:205], v[18:21]
	v_mfma_f32_16x16x32_f16 v[6:9], v[218:221], v[210:213], v[6:9]
	v_mfma_f32_16x16x32_f16 v[2:5], v[226:229], v[210:213], v[2:5]
	v_mfma_f32_16x16x32_f16 v[54:57], v[222:225], v[176:179], v[54:57]
	v_mfma_f32_16x16x32_f16 v[50:53], v[230:233], v[176:179], v[50:53]
	v_mfma_f32_16x16x32_f16 v[38:41], v[222:225], v[184:187], v[38:41]
	v_mfma_f32_16x16x32_f16 v[34:37], v[230:233], v[184:187], v[34:37]
	v_mfma_f32_16x16x32_f16 v[22:25], v[222:225], v[206:209], v[22:25]
	v_mfma_f32_16x16x32_f16 v[18:21], v[230:233], v[206:209], v[18:21]
	v_mfma_f32_16x16x32_f16 v[6:9], v[222:225], v[214:217], v[6:9]
	v_mfma_f32_16x16x32_f16 v[2:5], v[230:233], v[214:217], v[2:5]
	s_setprio 0
	s_add_i32 s53, s53, 2
	s_add_u32 s22, s22, 0x100
	s_addc_u32 s23, s23, 0
	s_add_u32 s51, s51, 0x100
	s_addc_u32 s52, s52, 0
	s_cmp_gt_u32 s53, 61
	s_barrier
	s_cbranch_scc0 .LBB0_2542
	s_ashr_i32 s9, s8, 31
	s_lshl_b64 s[8:9], s[8:9], 8
	s_lshl_b32 s3, s2, 8
	v_lshl_add_u64 v[140:141], s[8:9], 0, v[132:133]
	s_ashr_i32 s8, s3, 31
	v_mov_b32_e32 v153, s8
	v_or_b32_e32 v152, s3, v134
	v_lshlrev_b64 v[154:155], 10, v[140:141]
	v_lshl_add_u64 v[156:157], v[154:155], 0, v[152:153]
	v_lshl_add_u64 v[154:155], v[156:157], 1, s[10:11]
	global_load_dwordx4 v[166:169], v[154:155], off
	global_load_dwordx4 v[170:173], v[154:155], off offset:256
	s_mov_b32 s9, 0
	s_mov_b32 s8, 0x8000
	v_lshl_add_u64 v[234:235], v[154:155], 0, s[8:9]
	global_load_dwordx4 v[174:177], v[234:235], off
	global_load_dwordx4 v[178:181], v[234:235], off offset:256
	s_mov_b32 s8, 0x10000
	v_lshl_add_u64 v[234:235], v[154:155], 0, s[8:9]
	global_load_dwordx4 v[182:185], v[234:235], off
	global_load_dwordx4 v[186:189], v[234:235], off offset:256
	s_mov_b32 s8, 0x18000
	v_lshl_add_u64 v[234:235], v[154:155], 0, s[8:9]
	global_load_dwordx4 v[202:205], v[234:235], off
	global_load_dwordx4 v[206:209], v[234:235], off offset:256
	s_mov_b32 s8, 0x40000
	v_lshl_add_u64 v[234:235], v[154:155], 0, s[8:9]
	global_load_dwordx4 v[210:213], v[234:235], off
	global_load_dwordx4 v[214:217], v[234:235], off offset:256
	s_mov_b32 s8, 0x48000
	v_lshl_add_u64 v[234:235], v[154:155], 0, s[8:9]
	global_load_dwordx4 v[218:221], v[234:235], off
	global_load_dwordx4 v[222:225], v[234:235], off offset:256
	s_mov_b32 s8, 0x50000
	v_lshl_add_u64 v[234:235], v[154:155], 0, s[8:9]
	global_load_dwordx4 v[226:229], v[234:235], off
	global_load_dwordx4 v[230:233], v[234:235], off offset:256
	s_mov_b64 s[8:9], -1
	s_and_b64 vcc, exec, s[0:1]
	s_waitcnt vmcnt(13)
	v_cvt_f32_f16_e32 v164, v166
	v_cvt_f32_f16_sdwa v165, v166 dst_sel:DWORD dst_unused:UNUSED_PAD src0_sel:WORD_1
	v_cvt_f32_f16_e32 v160, v167
	v_cvt_f32_f16_sdwa v161, v167 dst_sel:DWORD dst_unused:UNUSED_PAD src0_sel:WORD_1
	v_pk_add_f32 v[126:127], v[126:127], v[164:165]
	v_cvt_f32_f16_e32 v164, v168
	v_cvt_f32_f16_sdwa v165, v168 dst_sel:DWORD dst_unused:UNUSED_PAD src0_sel:WORD_1
	v_pk_add_f32 v[128:129], v[128:129], v[160:161]
	v_cvt_f32_f16_e32 v160, v169
	v_cvt_f32_f16_sdwa v161, v169 dst_sel:DWORD dst_unused:UNUSED_PAD src0_sel:WORD_1
	v_pk_add_f32 v[122:123], v[122:123], v[164:165]
	v_pk_add_f32 v[124:125], v[124:125], v[160:161]
	s_cbranch_vccz .LBB0_2545
	v_cvt_pk_f16_f32 v163, v124, v125
	v_cvt_pk_f16_f32 v162, v122, v123
	v_cvt_pk_f16_f32 v161, v128, v129
	v_cvt_pk_f16_f32 v160, v126, v127
	global_store_dwordx4 v[154:155], v[160:163], off
	s_mov_b64 s[8:9], 0

;   __device__ __forceinline__ void operator()(const f32x4 (&acc)[2][2][4][2], const g8::Unit& u, int ui, int wr, int wc, int fr, int fq) const {
;     ...
;           const size_t idx = base + 128 * bj;
;           const h16x8 xv = *(const h16x8*)(xb + idx);
;           f32x4 x0 = acc[ai][bj][m][0], x1 = acc[ai][bj][m][1];
; #pragma unroll
;           for (int j = 0; j < 4; ++j) { x0[j] += (float)xv[j]; x1[j] += (float)xv[4 + j]; ss += x0[j] * x0[j] + x1[j] * x1[j]; }
;           if (final_out) {
;             __builtin_nontemporal_store(x0, (f32x4*)(xo + idx));
;             __builtin_nontemporal_store(x1, (f32x4*)(xo + idx + 4));
;           } else {
;             *(h16x8*)(xb + idx) = pack8(x0, x1);
;           }
.LBB0_2547:
	v_lshlrev_b64 v[156:157], 1, v[156:157]
	v_or_b32_e32 v156, 0x100, v156
	v_lshl_add_u64 v[156:157], s[10:11], 0, v[156:157]
	s_nop 0
	v_cndmask_b32_e64 v159, 0, 1, s[0:1]
	s_mov_b64 s[22:23], -1
	v_cmp_ne_u32_e64 s[8:9], 1, v159
	s_andn2_b64 vcc, exec, s[0:1]
	s_waitcnt vmcnt(13)
	v_cvt_f32_f16_e32 v164, v170
	v_cvt_f32_f16_sdwa v165, v170 dst_sel:DWORD dst_unused:UNUSED_PAD src0_sel:WORD_1
	v_cvt_f32_f16_e32 v160, v171
	v_cvt_f32_f16_sdwa v161, v171 dst_sel:DWORD dst_unused:UNUSED_PAD src0_sel:WORD_1
	v_pk_add_f32 v[118:119], v[118:119], v[164:165]
	v_cvt_f32_f16_e32 v164, v172
	v_cvt_f32_f16_sdwa v165, v172 dst_sel:DWORD dst_unused:UNUSED_PAD src0_sel:WORD_1
	v_pk_add_f32 v[120:121], v[120:121], v[160:161]
	v_cvt_f32_f16_e32 v160, v173
	v_cvt_f32_f16_sdwa v161, v173 dst_sel:DWORD dst_unused:UNUSED_PAD src0_sel:WORD_1
	v_pk_add_f32 v[114:115], v[114:115], v[164:165]
	v_pk_add_f32 v[116:117], v[116:117], v[160:161]
	s_cbranch_vccnz .LBB0_2549
	v_cvt_pk_f16_f32 v163, v116, v117
	v_cvt_pk_f16_f32 v162, v114, v115
	v_cvt_pk_f16_f32 v161, v120, v121
	v_cvt_pk_f16_f32 v160, v118, v119
	s_mov_b64 s[22:23], 0
	global_store_dwordx4 v[156:157], v[160:163], off

;   __device__ __forceinline__ void operator()(const f32x4 (&acc)[2][2][4][2], const g8::Unit& u, int ui, int wr, int wc, int fr, int fq) const {
;     ...
;           const size_t idx = base + 128 * bj;
;           const h16x8 xv = *(const h16x8*)(xb + idx);
;           f32x4 x0 = acc[ai][bj][m][0], x1 = acc[ai][bj][m][1];
; #pragma unroll
;           for (int j = 0; j < 4; ++j) { x0[j] += (float)xv[j]; x1[j] += (float)xv[4 + j]; ss += x0[j] * x0[j] + x1[j] * x1[j]; }
;           if (final_out) {
;             __builtin_nontemporal_store(x0, (f32x4*)(xo + idx));
;             __builtin_nontemporal_store(x1, (f32x4*)(xo + idx + 4));
;           } else {
;             *(h16x8*)(xb + idx) = pack8(x0, x1);
;           }
.LBB0_2553:
	s_or_b64 exec, exec, s[24:25]
	v_or_b32_e32 v114, 16, v140
	s_waitcnt lgkmcnt(0)
	v_mov_b32_e32 v115, v141
	v_lshlrev_b64 v[116:117], 10, v[114:115]
	v_lshl_add_u64 v[118:119], v[116:117], 0, v[152:153]
	v_lshl_add_u64 v[116:117], v[118:119], 1, s[10:11]
	s_nop 0
	s_mov_b64 s[24:25], -1
	s_and_b64 vcc, exec, s[8:9]
	s_waitcnt vmcnt(13)
	v_cvt_f32_f16_e32 v126, v174
	v_cvt_f32_f16_sdwa v127, v174 dst_sel:DWORD dst_unused:UNUSED_PAD src0_sel:WORD_1
	v_cvt_f32_f16_e32 v122, v175
	v_cvt_f32_f16_sdwa v123, v175 dst_sel:DWORD dst_unused:UNUSED_PAD src0_sel:WORD_1
	v_pk_add_f32 v[110:111], v[110:111], v[126:127]
	v_cvt_f32_f16_e32 v126, v176
	v_cvt_f32_f16_sdwa v127, v176 dst_sel:DWORD dst_unused:UNUSED_PAD src0_sel:WORD_1
	v_pk_add_f32 v[112:113], v[112:113], v[122:123]
	v_cvt_f32_f16_e32 v122, v177
	v_cvt_f32_f16_sdwa v123, v177 dst_sel:DWORD dst_unused:UNUSED_PAD src0_sel:WORD_1
	v_pk_add_f32 v[106:107], v[106:107], v[126:127]
	v_pk_add_f32 v[108:109], v[108:109], v[122:123]
	s_cbranch_vccnz .LBB0_2555
	v_cvt_pk_f16_f32 v125, v108, v109
	v_cvt_pk_f16_f32 v124, v106, v107
	v_cvt_pk_f16_f32 v123, v112, v113
	v_cvt_pk_f16_f32 v122, v110, v111
	s_mov_b64 s[24:25], 0
	global_store_dwordx4 v[116:117], v[122:125], off

;   __device__ __forceinline__ void operator()(const f32x4 (&acc)[2][2][4][2], const g8::Unit& u, int ui, int wr, int wc, int fr, int fq) const {
;     ...
;           const size_t idx = base + 128 * bj;
;           const h16x8 xv = *(const h16x8*)(xb + idx);
;           f32x4 x0 = acc[ai][bj][m][0], x1 = acc[ai][bj][m][1];
; #pragma unroll
;           for (int j = 0; j < 4; ++j) { x0[j] += (float)xv[j]; x1[j] += (float)xv[4 + j]; ss += x0[j] * x0[j] + x1[j] * x1[j]; }
;           if (final_out) {
;             __builtin_nontemporal_store(x0, (f32x4*)(xo + idx));
;             __builtin_nontemporal_store(x1, (f32x4*)(xo + idx + 4));
;           } else {
;             *(h16x8*)(xb + idx) = pack8(x0, x1);
;           }
.LBB0_2557:
	v_lshlrev_b64 v[118:119], 1, v[118:119]
	v_or_b32_e32 v118, 0x100, v118
	v_lshl_add_u64 v[118:119], s[10:11], 0, v[118:119]
	s_nop 0
	s_mov_b64 s[24:25], -1
	s_and_b64 vcc, exec, s[8:9]
	s_waitcnt vmcnt(13)
	v_cvt_f32_f16_e32 v126, v178
	v_cvt_f32_f16_sdwa v127, v178 dst_sel:DWORD dst_unused:UNUSED_PAD src0_sel:WORD_1
	v_cvt_f32_f16_e32 v122, v179
	v_cvt_f32_f16_sdwa v123, v179 dst_sel:DWORD dst_unused:UNUSED_PAD src0_sel:WORD_1
	v_pk_add_f32 v[102:103], v[102:103], v[126:127]
	v_cvt_f32_f16_e32 v126, v180
	v_cvt_f32_f16_sdwa v127, v180 dst_sel:DWORD dst_unused:UNUSED_PAD src0_sel:WORD_1
	v_pk_add_f32 v[104:105], v[104:105], v[122:123]
	v_cvt_f32_f16_e32 v122, v181
	v_cvt_f32_f16_sdwa v123, v181 dst_sel:DWORD dst_unused:UNUSED_PAD src0_sel:WORD_1
	v_pk_add_f32 v[98:99], v[98:99], v[126:127]
	v_pk_add_f32 v[100:101], v[100:101], v[122:123]
	s_cbranch_vccnz .LBB0_2559
	v_cvt_pk_f16_f32 v125, v100, v101
	v_cvt_pk_f16_f32 v124, v98, v99
	v_cvt_pk_f16_f32 v123, v104, v105
	v_cvt_pk_f16_f32 v122, v102, v103
	s_mov_b64 s[24:25], 0
	global_store_dwordx4 v[118:119], v[122:125], off

;   __device__ __forceinline__ void operator()(const f32x4 (&acc)[2][2][4][2], const g8::Unit& u, int ui, int wr, int wc, int fr, int fq) const {
;     ...
;           const size_t idx = base + 128 * bj;
;           const h16x8 xv = *(const h16x8*)(xb + idx);
;           f32x4 x0 = acc[ai][bj][m][0], x1 = acc[ai][bj][m][1];
; #pragma unroll
;           for (int j = 0; j < 4; ++j) { x0[j] += (float)xv[j]; x1[j] += (float)xv[4 + j]; ss += x0[j] * x0[j] + x1[j] * x1[j]; }
;           if (final_out) {
;             __builtin_nontemporal_store(x0, (f32x4*)(xo + idx));
;             __builtin_nontemporal_store(x1, (f32x4*)(xo + idx + 4));
;           } else {
;             *(h16x8*)(xb + idx) = pack8(x0, x1);
;           }
.LBB0_2563:
	s_or_b64 exec, exec, s[24:25]
	v_or_b32_e32 v98, 32, v140
	s_waitcnt lgkmcnt(0)
	v_mov_b32_e32 v99, v141
	v_lshlrev_b64 v[100:101], 10, v[98:99]
	v_lshl_add_u64 v[102:103], v[100:101], 0, v[152:153]
	v_lshl_add_u64 v[100:101], v[102:103], 1, s[10:11]
	s_nop 0
	s_mov_b64 s[24:25], -1
	s_and_b64 vcc, exec, s[8:9]
	s_waitcnt vmcnt(13)
	v_cvt_f32_f16_e32 v108, v182
	v_cvt_f32_f16_sdwa v109, v182 dst_sel:DWORD dst_unused:UNUSED_PAD src0_sel:WORD_1
	v_cvt_f32_f16_e32 v104, v183
	v_cvt_f32_f16_sdwa v105, v183 dst_sel:DWORD dst_unused:UNUSED_PAD src0_sel:WORD_1
	v_pk_add_f32 v[94:95], v[94:95], v[108:109]
	v_cvt_f32_f16_e32 v108, v184
	v_cvt_f32_f16_sdwa v109, v184 dst_sel:DWORD dst_unused:UNUSED_PAD src0_sel:WORD_1
	v_pk_add_f32 v[96:97], v[96:97], v[104:105]
	v_cvt_f32_f16_e32 v104, v185
	v_cvt_f32_f16_sdwa v105, v185 dst_sel:DWORD dst_unused:UNUSED_PAD src0_sel:WORD_1
	v_pk_add_f32 v[90:91], v[90:91], v[108:109]
	v_pk_add_f32 v[92:93], v[92:93], v[104:105]
	s_cbranch_vccnz .LBB0_2565
	v_cvt_pk_f16_f32 v107, v92, v93
	v_cvt_pk_f16_f32 v106, v90, v91
	v_cvt_pk_f16_f32 v105, v96, v97
	v_cvt_pk_f16_f32 v104, v94, v95
	s_mov_b64 s[24:25], 0
	global_store_dwordx4 v[100:101], v[104:107], off

;   __device__ __forceinline__ void operator()(const f32x4 (&acc)[2][2][4][2], const g8::Unit& u, int ui, int wr, int wc, int fr, int fq) const {
;     ...
;           const size_t idx = base + 128 * bj;
;           const h16x8 xv = *(const h16x8*)(xb + idx);
;           f32x4 x0 = acc[ai][bj][m][0], x1 = acc[ai][bj][m][1];
; #pragma unroll
;           for (int j = 0; j < 4; ++j) { x0[j] += (float)xv[j]; x1[j] += (float)xv[4 + j]; ss += x0[j] * x0[j] + x1[j] * x1[j]; }
;           if (final_out) {
;             __builtin_nontemporal_store(x0, (f32x4*)(xo + idx));
;             __builtin_nontemporal_store(x1, (f32x4*)(xo + idx + 4));
;           } else {
;             *(h16x8*)(xb + idx) = pack8(x0, x1);
;           }
.LBB0_2567:
	v_lshlrev_b64 v[102:103], 1, v[102:103]
	v_or_b32_e32 v102, 0x100, v102
	v_lshl_add_u64 v[102:103], s[10:11], 0, v[102:103]
	s_nop 0
	s_mov_b64 s[24:25], -1
	s_and_b64 vcc, exec, s[8:9]
	s_waitcnt vmcnt(13)
	v_cvt_f32_f16_e32 v108, v186
	v_cvt_f32_f16_sdwa v109, v186 dst_sel:DWORD dst_unused:UNUSED_PAD src0_sel:WORD_1
	v_cvt_f32_f16_e32 v104, v187
	v_cvt_f32_f16_sdwa v105, v187 dst_sel:DWORD dst_unused:UNUSED_PAD src0_sel:WORD_1
	v_pk_add_f32 v[86:87], v[86:87], v[108:109]
	v_cvt_f32_f16_e32 v108, v188
	v_cvt_f32_f16_sdwa v109, v188 dst_sel:DWORD dst_unused:UNUSED_PAD src0_sel:WORD_1
	v_pk_add_f32 v[88:89], v[88:89], v[104:105]
	v_cvt_f32_f16_e32 v104, v189
	v_cvt_f32_f16_sdwa v105, v189 dst_sel:DWORD dst_unused:UNUSED_PAD src0_sel:WORD_1
	v_pk_add_f32 v[82:83], v[82:83], v[108:109]
	v_pk_add_f32 v[84:85], v[84:85], v[104:105]
	s_cbranch_vccnz .LBB0_2569
	v_cvt_pk_f16_f32 v107, v84, v85
	v_cvt_pk_f16_f32 v106, v82, v83
	v_cvt_pk_f16_f32 v105, v88, v89
	v_cvt_pk_f16_f32 v104, v86, v87
	s_mov_b64 s[24:25], 0
	global_store_dwordx4 v[102:103], v[104:107], off

;   __device__ __forceinline__ void operator()(const f32x4 (&acc)[2][2][4][2], const g8::Unit& u, int ui, int wr, int wc, int fr, int fq) const {
;     ...
;           const size_t idx = base + 128 * bj;
;           const h16x8 xv = *(const h16x8*)(xb + idx);
;           f32x4 x0 = acc[ai][bj][m][0], x1 = acc[ai][bj][m][1];
; #pragma unroll
;           for (int j = 0; j < 4; ++j) { x0[j] += (float)xv[j]; x1[j] += (float)xv[4 + j]; ss += x0[j] * x0[j] + x1[j] * x1[j]; }
;           if (final_out) {
;             __builtin_nontemporal_store(x0, (f32x4*)(xo + idx));
;             __builtin_nontemporal_store(x1, (f32x4*)(xo + idx + 4));
;           } else {
;             *(h16x8*)(xb + idx) = pack8(x0, x1);
;           }
.LBB0_2573:
	s_or_b64 exec, exec, s[24:25]
	v_or_b32_e32 v82, 48, v140
	s_waitcnt lgkmcnt(0)
	v_mov_b32_e32 v83, v141
	v_lshlrev_b64 v[84:85], 10, v[82:83]
	v_lshl_add_u64 v[86:87], v[84:85], 0, v[152:153]
	v_lshl_add_u64 v[84:85], v[86:87], 1, s[10:11]
	s_nop 0
	s_mov_b64 s[24:25], -1
	s_and_b64 vcc, exec, s[8:9]
	s_waitcnt vmcnt(13)
	v_cvt_f32_f16_e32 v92, v202
	v_cvt_f32_f16_sdwa v93, v202 dst_sel:DWORD dst_unused:UNUSED_PAD src0_sel:WORD_1
	v_cvt_f32_f16_e32 v88, v203
	v_cvt_f32_f16_sdwa v89, v203 dst_sel:DWORD dst_unused:UNUSED_PAD src0_sel:WORD_1
	v_pk_add_f32 v[78:79], v[78:79], v[92:93]
	v_cvt_f32_f16_e32 v92, v204
	v_cvt_f32_f16_sdwa v93, v204 dst_sel:DWORD dst_unused:UNUSED_PAD src0_sel:WORD_1
	v_pk_add_f32 v[80:81], v[80:81], v[88:89]
	v_cvt_f32_f16_e32 v88, v205
	v_cvt_f32_f16_sdwa v89, v205 dst_sel:DWORD dst_unused:UNUSED_PAD src0_sel:WORD_1
	v_pk_add_f32 v[74:75], v[74:75], v[92:93]
	v_pk_add_f32 v[76:77], v[76:77], v[88:89]
	s_cbranch_vccnz .LBB0_2575
	v_cvt_pk_f16_f32 v91, v76, v77
	v_cvt_pk_f16_f32 v90, v74, v75
	v_cvt_pk_f16_f32 v89, v80, v81
	v_cvt_pk_f16_f32 v88, v78, v79
	s_mov_b64 s[24:25], 0
	global_store_dwordx4 v[84:85], v[88:91], off

;   __device__ __forceinline__ void operator()(const f32x4 (&acc)[2][2][4][2], const g8::Unit& u, int ui, int wr, int wc, int fr, int fq) const {
;     ...
;           const size_t idx = base + 128 * bj;
;           const h16x8 xv = *(const h16x8*)(xb + idx);
;           f32x4 x0 = acc[ai][bj][m][0], x1 = acc[ai][bj][m][1];
; #pragma unroll
;           for (int j = 0; j < 4; ++j) { x0[j] += (float)xv[j]; x1[j] += (float)xv[4 + j]; ss += x0[j] * x0[j] + x1[j] * x1[j]; }
;           if (final_out) {
;             __builtin_nontemporal_store(x0, (f32x4*)(xo + idx));
;             __builtin_nontemporal_store(x1, (f32x4*)(xo + idx + 4));
;           } else {
;             *(h16x8*)(xb + idx) = pack8(x0, x1);
;           }
.LBB0_2577:
	v_lshlrev_b64 v[86:87], 1, v[86:87]
	v_or_b32_e32 v86, 0x100, v86
	v_lshl_add_u64 v[86:87], s[10:11], 0, v[86:87]
	s_nop 0
	s_mov_b64 s[24:25], -1
	s_and_b64 vcc, exec, s[8:9]
	s_waitcnt vmcnt(13)
	v_cvt_f32_f16_e32 v92, v206
	v_cvt_f32_f16_sdwa v93, v206 dst_sel:DWORD dst_unused:UNUSED_PAD src0_sel:WORD_1
	v_cvt_f32_f16_e32 v88, v207
	v_cvt_f32_f16_sdwa v89, v207 dst_sel:DWORD dst_unused:UNUSED_PAD src0_sel:WORD_1
	v_pk_add_f32 v[70:71], v[70:71], v[92:93]
	v_cvt_f32_f16_e32 v92, v208
	v_cvt_f32_f16_sdwa v93, v208 dst_sel:DWORD dst_unused:UNUSED_PAD src0_sel:WORD_1
	v_pk_add_f32 v[72:73], v[72:73], v[88:89]
	v_cvt_f32_f16_e32 v88, v209
	v_cvt_f32_f16_sdwa v89, v209 dst_sel:DWORD dst_unused:UNUSED_PAD src0_sel:WORD_1
	v_pk_add_f32 v[66:67], v[66:67], v[92:93]
	v_pk_add_f32 v[68:69], v[68:69], v[88:89]
	s_cbranch_vccnz .LBB0_2579
	v_cvt_pk_f16_f32 v91, v68, v69
	v_cvt_pk_f16_f32 v90, v66, v67
	v_cvt_pk_f16_f32 v89, v72, v73
	v_cvt_pk_f16_f32 v88, v70, v71
	s_mov_b64 s[24:25], 0
	global_store_dwordx4 v[86:87], v[88:91], off

;   __device__ __forceinline__ void operator()(const f32x4 (&acc)[2][2][4][2], const g8::Unit& u, int ui, int wr, int wc, int fr, int fq) const {
;     ...
;           const size_t idx = base + 128 * bj;
;           const h16x8 xv = *(const h16x8*)(xb + idx);
;           f32x4 x0 = acc[ai][bj][m][0], x1 = acc[ai][bj][m][1];
; #pragma unroll
;           for (int j = 0; j < 4; ++j) { x0[j] += (float)xv[j]; x1[j] += (float)xv[4 + j]; ss += x0[j] * x0[j] + x1[j] * x1[j]; }
;           if (final_out) {
;             __builtin_nontemporal_store(x0, (f32x4*)(xo + idx));
;             __builtin_nontemporal_store(x1, (f32x4*)(xo + idx + 4));
;           } else {
;             *(h16x8*)(xb + idx) = pack8(x0, x1);
;           }
.LBB0_2583:
	s_or_b64 exec, exec, s[24:25]
	s_waitcnt lgkmcnt(0)
	v_lshl_add_u64 v[66:67], v[140:141], 0, s[94:95]
	v_lshlrev_b64 v[68:69], 10, v[66:67]
	v_lshl_add_u64 v[70:71], v[68:69], 0, v[152:153]
	v_lshl_add_u64 v[68:69], v[70:71], 1, s[10:11]
	s_nop 0
	s_mov_b64 s[24:25], -1
	s_and_b64 vcc, exec, s[8:9]
	s_waitcnt vmcnt(13)
	v_cvt_f32_f16_e32 v76, v210
	v_cvt_f32_f16_sdwa v77, v210 dst_sel:DWORD dst_unused:UNUSED_PAD src0_sel:WORD_1
	v_cvt_f32_f16_e32 v72, v211
	v_cvt_f32_f16_sdwa v73, v211 dst_sel:DWORD dst_unused:UNUSED_PAD src0_sel:WORD_1
	v_pk_add_f32 v[62:63], v[62:63], v[76:77]
	v_cvt_f32_f16_e32 v76, v212
	v_cvt_f32_f16_sdwa v77, v212 dst_sel:DWORD dst_unused:UNUSED_PAD src0_sel:WORD_1
	v_pk_add_f32 v[64:65], v[64:65], v[72:73]
	v_cvt_f32_f16_e32 v72, v213
	v_cvt_f32_f16_sdwa v73, v213 dst_sel:DWORD dst_unused:UNUSED_PAD src0_sel:WORD_1
	v_pk_add_f32 v[58:59], v[58:59], v[76:77]
	v_pk_add_f32 v[60:61], v[60:61], v[72:73]
	s_cbranch_vccnz .LBB0_2585
	v_cvt_pk_f16_f32 v75, v60, v61
	v_cvt_pk_f16_f32 v74, v58, v59
	v_cvt_pk_f16_f32 v73, v64, v65
	v_cvt_pk_f16_f32 v72, v62, v63
	s_mov_b64 s[24:25], 0
	global_store_dwordx4 v[68:69], v[72:75], off

;   __device__ __forceinline__ void operator()(const f32x4 (&acc)[2][2][4][2], const g8::Unit& u, int ui, int wr, int wc, int fr, int fq) const {
;     ...
;           const size_t idx = base + 128 * bj;
;           const h16x8 xv = *(const h16x8*)(xb + idx);
;           f32x4 x0 = acc[ai][bj][m][0], x1 = acc[ai][bj][m][1];
; #pragma unroll
;           for (int j = 0; j < 4; ++j) { x0[j] += (float)xv[j]; x1[j] += (float)xv[4 + j]; ss += x0[j] * x0[j] + x1[j] * x1[j]; }
;           if (final_out) {
;             __builtin_nontemporal_store(x0, (f32x4*)(xo + idx));
;             __builtin_nontemporal_store(x1, (f32x4*)(xo + idx + 4));
;           } else {
;             *(h16x8*)(xb + idx) = pack8(x0, x1);
;           }
.LBB0_2587:
	v_lshlrev_b64 v[70:71], 1, v[70:71]
	v_or_b32_e32 v70, 0x100, v70
	v_lshl_add_u64 v[70:71], s[10:11], 0, v[70:71]
	s_nop 0
	s_mov_b64 s[24:25], -1
	s_and_b64 vcc, exec, s[8:9]
	s_waitcnt vmcnt(13)
	v_cvt_f32_f16_e32 v76, v214
	v_cvt_f32_f16_sdwa v77, v214 dst_sel:DWORD dst_unused:UNUSED_PAD src0_sel:WORD_1
	v_cvt_f32_f16_e32 v72, v215
	v_cvt_f32_f16_sdwa v73, v215 dst_sel:DWORD dst_unused:UNUSED_PAD src0_sel:WORD_1
	v_pk_add_f32 v[54:55], v[54:55], v[76:77]
	v_cvt_f32_f16_e32 v76, v216
	v_cvt_f32_f16_sdwa v77, v216 dst_sel:DWORD dst_unused:UNUSED_PAD src0_sel:WORD_1
	v_pk_add_f32 v[56:57], v[56:57], v[72:73]
	v_cvt_f32_f16_e32 v72, v217
	v_cvt_f32_f16_sdwa v73, v217 dst_sel:DWORD dst_unused:UNUSED_PAD src0_sel:WORD_1
	v_pk_add_f32 v[50:51], v[50:51], v[76:77]
	v_pk_add_f32 v[52:53], v[52:53], v[72:73]
	s_cbranch_vccnz .LBB0_2589
	v_cvt_pk_f16_f32 v75, v52, v53
	v_cvt_pk_f16_f32 v74, v50, v51
	v_cvt_pk_f16_f32 v73, v56, v57
	v_cvt_pk_f16_f32 v72, v54, v55
	s_mov_b64 s[24:25], 0
	global_store_dwordx4 v[70:71], v[72:75], off

;   __device__ __forceinline__ void operator()(const f32x4 (&acc)[2][2][4][2], const g8::Unit& u, int ui, int wr, int wc, int fr, int fq) const {
;     ...
;           const size_t idx = base + 128 * bj;
;           const h16x8 xv = *(const h16x8*)(xb + idx);
;           f32x4 x0 = acc[ai][bj][m][0], x1 = acc[ai][bj][m][1];
; #pragma unroll
;           for (int j = 0; j < 4; ++j) { x0[j] += (float)xv[j]; x1[j] += (float)xv[4 + j]; ss += x0[j] * x0[j] + x1[j] * x1[j]; }
;           if (final_out) {
;             __builtin_nontemporal_store(x0, (f32x4*)(xo + idx));
;             __builtin_nontemporal_store(x1, (f32x4*)(xo + idx + 4));
;           } else {
;             *(h16x8*)(xb + idx) = pack8(x0, x1);
;           }
.LBB0_2593:
	s_or_b64 exec, exec, s[24:25]
	s_mov_b64 s[2:3], 0x90
	s_waitcnt lgkmcnt(0)
	v_lshl_add_u64 v[50:51], v[140:141], 0, s[2:3]
	v_lshlrev_b64 v[52:53], 10, v[50:51]
	v_lshl_add_u64 v[54:55], v[52:53], 0, v[152:153]
	v_lshl_add_u64 v[52:53], v[54:55], 1, s[10:11]
	s_nop 0
	s_mov_b64 s[24:25], -1
	s_and_b64 vcc, exec, s[8:9]
	s_waitcnt vmcnt(13)
	v_cvt_f32_f16_e32 v60, v218
	v_cvt_f32_f16_sdwa v61, v218 dst_sel:DWORD dst_unused:UNUSED_PAD src0_sel:WORD_1
	v_cvt_f32_f16_e32 v56, v219
	v_cvt_f32_f16_sdwa v57, v219 dst_sel:DWORD dst_unused:UNUSED_PAD src0_sel:WORD_1
	v_pk_add_f32 v[46:47], v[46:47], v[60:61]
	v_cvt_f32_f16_e32 v60, v220
	v_cvt_f32_f16_sdwa v61, v220 dst_sel:DWORD dst_unused:UNUSED_PAD src0_sel:WORD_1
	v_pk_add_f32 v[48:49], v[48:49], v[56:57]
	v_cvt_f32_f16_e32 v56, v221
	v_cvt_f32_f16_sdwa v57, v221 dst_sel:DWORD dst_unused:UNUSED_PAD src0_sel:WORD_1
	v_pk_add_f32 v[42:43], v[42:43], v[60:61]
	v_pk_add_f32 v[44:45], v[44:45], v[56:57]
	s_cbranch_vccnz .LBB0_2595
	v_cvt_pk_f16_f32 v59, v44, v45
	v_cvt_pk_f16_f32 v58, v42, v43
	v_cvt_pk_f16_f32 v57, v48, v49
	v_cvt_pk_f16_f32 v56, v46, v47
	s_mov_b64 s[24:25], 0
	global_store_dwordx4 v[52:53], v[56:59], off

;   __device__ __forceinline__ void operator()(const f32x4 (&acc)[2][2][4][2], const g8::Unit& u, int ui, int wr, int wc, int fr, int fq) const {
;     ...
;           const size_t idx = base + 128 * bj;
;           const h16x8 xv = *(const h16x8*)(xb + idx);
;           f32x4 x0 = acc[ai][bj][m][0], x1 = acc[ai][bj][m][1];
; #pragma unroll
;           for (int j = 0; j < 4; ++j) { x0[j] += (float)xv[j]; x1[j] += (float)xv[4 + j]; ss += x0[j] * x0[j] + x1[j] * x1[j]; }
;           if (final_out) {
;             __builtin_nontemporal_store(x0, (f32x4*)(xo + idx));
;             __builtin_nontemporal_store(x1, (f32x4*)(xo + idx + 4));
;           } else {
;             *(h16x8*)(xb + idx) = pack8(x0, x1);
;           }
.LBB0_2597:
	v_lshlrev_b64 v[54:55], 1, v[54:55]
	v_or_b32_e32 v54, 0x100, v54
	v_lshl_add_u64 v[54:55], s[10:11], 0, v[54:55]
	s_nop 0
	s_mov_b64 s[24:25], -1
	s_and_b64 vcc, exec, s[8:9]
	s_waitcnt vmcnt(13)
	v_cvt_f32_f16_e32 v60, v222
	v_cvt_f32_f16_sdwa v61, v222 dst_sel:DWORD dst_unused:UNUSED_PAD src0_sel:WORD_1
	v_cvt_f32_f16_e32 v56, v223
	v_cvt_f32_f16_sdwa v57, v223 dst_sel:DWORD dst_unused:UNUSED_PAD src0_sel:WORD_1
	v_pk_add_f32 v[38:39], v[38:39], v[60:61]
	v_cvt_f32_f16_e32 v60, v224
	v_cvt_f32_f16_sdwa v61, v224 dst_sel:DWORD dst_unused:UNUSED_PAD src0_sel:WORD_1
	v_pk_add_f32 v[40:41], v[40:41], v[56:57]
	v_cvt_f32_f16_e32 v56, v225
	v_cvt_f32_f16_sdwa v57, v225 dst_sel:DWORD dst_unused:UNUSED_PAD src0_sel:WORD_1
	v_pk_add_f32 v[34:35], v[34:35], v[60:61]
	v_pk_add_f32 v[36:37], v[36:37], v[56:57]
	s_cbranch_vccnz .LBB0_2599
	v_cvt_pk_f16_f32 v59, v36, v37
	v_cvt_pk_f16_f32 v58, v34, v35
	v_cvt_pk_f16_f32 v57, v40, v41
	v_cvt_pk_f16_f32 v56, v38, v39
	s_mov_b64 s[24:25], 0
	global_store_dwordx4 v[54:55], v[56:59], off

;   __device__ __forceinline__ void operator()(const f32x4 (&acc)[2][2][4][2], const g8::Unit& u, int ui, int wr, int wc, int fr, int fq) const {
;     ...
;           const size_t idx = base + 128 * bj;
;           const h16x8 xv = *(const h16x8*)(xb + idx);
;           f32x4 x0 = acc[ai][bj][m][0], x1 = acc[ai][bj][m][1];
; #pragma unroll
;           for (int j = 0; j < 4; ++j) { x0[j] += (float)xv[j]; x1[j] += (float)xv[4 + j]; ss += x0[j] * x0[j] + x1[j] * x1[j]; }
;           if (final_out) {
;             __builtin_nontemporal_store(x0, (f32x4*)(xo + idx));
;             __builtin_nontemporal_store(x1, (f32x4*)(xo + idx + 4));
;           } else {
;             *(h16x8*)(xb + idx) = pack8(x0, x1);
;           }
.LBB0_2603:
	s_or_b64 exec, exec, s[24:25]
	s_mov_b64 s[2:3], 0xa0
	s_waitcnt lgkmcnt(0)
	v_lshl_add_u64 v[34:35], v[140:141], 0, s[2:3]
	v_lshlrev_b64 v[36:37], 10, v[34:35]
	v_lshl_add_u64 v[38:39], v[36:37], 0, v[152:153]
	v_lshl_add_u64 v[36:37], v[38:39], 1, s[10:11]
	s_nop 0
	s_mov_b64 s[24:25], -1
	s_and_b64 vcc, exec, s[8:9]
	s_waitcnt vmcnt(13)
	v_cvt_f32_f16_e32 v44, v226
	v_cvt_f32_f16_sdwa v45, v226 dst_sel:DWORD dst_unused:UNUSED_PAD src0_sel:WORD_1
	v_cvt_f32_f16_e32 v40, v227
	v_cvt_f32_f16_sdwa v41, v227 dst_sel:DWORD dst_unused:UNUSED_PAD src0_sel:WORD_1
	v_pk_add_f32 v[30:31], v[30:31], v[44:45]
	v_cvt_f32_f16_e32 v44, v228
	v_cvt_f32_f16_sdwa v45, v228 dst_sel:DWORD dst_unused:UNUSED_PAD src0_sel:WORD_1
	v_pk_add_f32 v[32:33], v[32:33], v[40:41]
	v_cvt_f32_f16_e32 v40, v229
	v_cvt_f32_f16_sdwa v41, v229 dst_sel:DWORD dst_unused:UNUSED_PAD src0_sel:WORD_1
	v_pk_add_f32 v[26:27], v[26:27], v[44:45]
	v_pk_add_f32 v[28:29], v[28:29], v[40:41]
	s_cbranch_vccnz .LBB0_2605
	v_cvt_pk_f16_f32 v43, v28, v29
	v_cvt_pk_f16_f32 v42, v26, v27
	v_cvt_pk_f16_f32 v41, v32, v33
	v_cvt_pk_f16_f32 v40, v30, v31
	s_mov_b64 s[24:25], 0
	global_store_dwordx4 v[36:37], v[40:43], off

;   __device__ __forceinline__ void operator()(const f32x4 (&acc)[2][2][4][2], const g8::Unit& u, int ui, int wr, int wc, int fr, int fq) const {
;     ...
;           const size_t idx = base + 128 * bj;
;           const h16x8 xv = *(const h16x8*)(xb + idx);
;           f32x4 x0 = acc[ai][bj][m][0], x1 = acc[ai][bj][m][1];
; #pragma unroll
;           for (int j = 0; j < 4; ++j) { x0[j] += (float)xv[j]; x1[j] += (float)xv[4 + j]; ss += x0[j] * x0[j] + x1[j] * x1[j]; }
;           if (final_out) {
;             __builtin_nontemporal_store(x0, (f32x4*)(xo + idx));
;             __builtin_nontemporal_store(x1, (f32x4*)(xo + idx + 4));
;           } else {
;             *(h16x8*)(xb + idx) = pack8(x0, x1);
;           }
.LBB0_2607:
	v_lshlrev_b64 v[38:39], 1, v[38:39]
	v_or_b32_e32 v38, 0x100, v38
	v_lshl_add_u64 v[38:39], s[10:11], 0, v[38:39]
	s_nop 0
	s_mov_b64 s[24:25], -1
	s_and_b64 vcc, exec, s[8:9]
	s_waitcnt vmcnt(13)
	v_cvt_f32_f16_e32 v44, v230
	v_cvt_f32_f16_sdwa v45, v230 dst_sel:DWORD dst_unused:UNUSED_PAD src0_sel:WORD_1
	v_cvt_f32_f16_e32 v40, v231
	v_cvt_f32_f16_sdwa v41, v231 dst_sel:DWORD dst_unused:UNUSED_PAD src0_sel:WORD_1
	v_pk_add_f32 v[22:23], v[22:23], v[44:45]
	v_cvt_f32_f16_e32 v44, v232
	v_cvt_f32_f16_sdwa v45, v232 dst_sel:DWORD dst_unused:UNUSED_PAD src0_sel:WORD_1
	v_pk_add_f32 v[24:25], v[24:25], v[40:41]
	v_cvt_f32_f16_e32 v40, v233
	v_cvt_f32_f16_sdwa v41, v233 dst_sel:DWORD dst_unused:UNUSED_PAD src0_sel:WORD_1
	v_pk_add_f32 v[18:19], v[18:19], v[44:45]
	v_pk_add_f32 v[20:21], v[20:21], v[40:41]
	s_cbranch_vccnz .LBB0_2609
	v_cvt_pk_f16_f32 v43, v20, v21
	v_cvt_pk_f16_f32 v42, v18, v19
	v_cvt_pk_f16_f32 v41, v24, v25
	v_cvt_pk_f16_f32 v40, v22, v23
	s_mov_b64 s[24:25], 0
	global_store_dwordx4 v[38:39], v[40:43], off
